# phase 2 load balance: workgroups owning a compress-GEMM tile do only that; their two conv tiles go to workgroups 64..191 as a third tile
# speedup vs baseline: 1.0160x; 1.0160x over previous
; DEVI void phase2(const Params& p, unsigned char* smem) {
;   u16* sA = (u16*)smem; u16* sB = sA + 128 * 72;
; #pragma unroll 1
;   for (int tile = blockIdx.x; tile < 64 + 1024; tile += gridDim.x) {
;     GEMM_LANE_VARS
;     if (tile < 64) {
.LBB0_548:
	s_cmp_gt_i32 s88, 2
	s_cselect_b64 s[0:1], -1, 0
	s_cmp_lt_i32 s89, 2
	s_cselect_b64 s[2:3], -1, 0
	s_or_b64 s[0:1], s[0:1], s[2:3]
	s_and_b64 vcc, exec, s[0:1]
	s_cbranch_vccnz .LBB0_748
	s_mov_b32 s96, 0
	s_cmpk_gt_i32 s90, 0x43f
	s_cbranch_scc1 .LBB0_694
	v_mbcnt_lo_u32_b32 v0, -1, 0
	v_mbcnt_hi_u32_b32 v199, -1, v0
	s_add_u32 s6, s68, 0x200
	v_and_b32_e32 v0, 64, v199
	s_addc_u32 s7, s69, 0
	v_mov_b32_e32 v65, 0
	s_movk_i32 s11, 0x1240
	s_waitcnt lgkmcnt(0)
	s_mov_b32 s24, 0xffff0000
	s_movk_i32 s25, 0x7fff
	s_mov_b32 s9, 0
	s_mov_b32 s10, 0x3b000000
	s_mov_b32 s28, 0x800000
	s_movk_i32 s29, 0x7f
	s_movk_i32 s30, 0x80
	s_movk_i32 s31, 0x1080
	s_mov_b32 s34, 0x920000
	s_mov_b64 s[12:13], 0x1240
	s_mov_b64 s[14:15], 0x80
	s_mov_b64 s[18:19], 0x2480
	s_mov_b64 s[20:21], 0x100
	v_mov_b32_e32 v198, 1
	v_add_u32_e32 v200, 64, v0
	v_xor_b32_e32 v201, 32, v199
	v_xor_b32_e32 v202, 16, v199
	v_xor_b32_e32 v203, 8, v199
	v_xor_b32_e32 v204, 4, v199
	v_xor_b32_e32 v205, 2, v199
	v_xor_b32_e32 v206, 1, v199
	v_mov_b32_e32 v207, 0x7e0
	s_mov_b32 s35, s90
	s_branch .LBB0_553

; DEVI void phase2(const Params& p, unsigned char* smem) {
;     ...
;   for (int tile = blockIdx.x; tile < 64 + 1024; tile += gridDim.x) {
.LBB0_552:
	s_load_dword s0, s[6:7], 0x0
	s_waitcnt lgkmcnt(0)
	s_add_i32 s35, s0, s35
	s_cmp_lg_u32 s0, 0x200
	s_cbranch_scc1 .Lp2_latch_plain
	s_cmp_lg_u32 s96, 0
	s_cbranch_scc1 .LBB0_694
	s_cmp_lt_u32 s90, 64
	s_cbranch_scc1 .LBB0_694
	s_add_u32 s1, s90, 0x400
	s_cmp_lg_u32 s35, s1
	s_cbranch_scc1 .Lp2_latch_plain
	s_cmp_ge_u32 s90, 0xc0
	s_cbranch_scc1 .Lp2_latch_plain
	s_mov_b32 s96, 1
	s_cmp_ge_u32 s90, 0x80
	s_cbranch_scc1 .Lp2_second_group
	s_sub_u32 s35, s35, 64
	s_branch .Lp2_latch_plain
.Lp2_second_group:
	s_sub_u32 s35, s35, 0x280
.Lp2_latch_plain:
	s_cmpk_lt_i32 s35, 0x440
	s_cbranch_scc0 .LBB0_694
